# attention unit-seam wait relaxed to the q loads only; peeled first K-iteration with relaxed waits; P1+P5 epilogue row-scale prefetch; P2a slot rotation
# baseline (speedup 1.0000x reference)
; #define GAS __attribute__((address_space(1)))
; __device__ __forceinline__ void at_dma_k(LAS unsigned char* kdst, const bf16_t* kbase, int tq0, int dil, int tile, int lane_) {
;     int lane = lane_; asm volatile("" : "+v"(lane));
;     const int r0 = lane >> 3; const unsigned c0 = (unsigned)(((lane & 7) ^ r0) << 4);
;     const int t0 = tq0 + dil * (32 * tile + r0 - 64), d8 = 8 * dil;
; #pragma unroll
;     for (int n = 0; n < 4; ++n) { int tkn = t0 + n * d8; tkn = tkn < 0 ? 0 : (tkn > SEQ - 1 ? SEQ - 1 : tkn);
;         const unsigned off = ((unsigned)tkn << 7) + c0;
;         __builtin_amdgcn_global_load_lds((const unsigned*)((const GAS char*)kbase + off), (LAS unsigned*)(kdst + n * 1024), 16, 0, 0); }
; }
; __device__ __forceinline__ long bf16x8_to_fp8(const bf16x8 v) {
;     const v4u w = __builtin_bit_cast(v4u, v);
;     int lo = __builtin_amdgcn_cvt_pk_fp8_f32(__builtin_bit_cast(float, w.x << 16), __builtin_bit_cast(float, w.x & 0xffff0000u), 0, false);
;     lo = __builtin_amdgcn_cvt_pk_fp8_f32(__builtin_bit_cast(float, w.y << 16), __builtin_bit_cast(float, w.y & 0xffff0000u), lo, true);
;     int hi = __builtin_amdgcn_cvt_pk_fp8_f32(__builtin_bit_cast(float, w.z << 16), __builtin_bit_cast(float, w.z & 0xffff0000u), 0, false);
;     hi = __builtin_amdgcn_cvt_pk_fp8_f32(__builtin_bit_cast(float, w.w << 16), __builtin_bit_cast(float, w.w & 0xffff0000u), hi, true);
;     return (long)(((unsigned long long)(unsigned)hi << 32) | (unsigned long long)(unsigned)lo);
; }
; __device__ __forceinline__ void at_dma_v(LAS unsigned char* vdst, const bf16_t* vbase, int tq0, int dil, int tile, int lane_) { at_dma_k(vdst, vbase, tq0, dil, tile, lane_); }
; template <int OFF> __device__ __forceinline__ long tr8_read(unsigned vb) {
;     long r; asm volatile("ds_read_b64_tr_b8 %0, %1 offset:%2" : "=&v"(r) : "v"(vb), "i"(OFF) : "memory"); return r;
; }
; __global__ void __launch_bounds__(NWAVES * 64, 2) mk_fwd(Args args) {
;     ...
;         int U = vwave;
;         if (U < NU) {
;             const bf16_t *cq, *ck, *cv, *nq, *nk, *nv; bf16_t *cp, *np_; float *cm, *nm; int ctq, cdl, ntq = 0, ndl = 1; float csl, nsl = 0.f;
;             AT_DEC_AB(U, cq, ck, cv, ctq, cdl, csl, cp, cm);
;             nq = cq; nk = ck; nv = cv; np_ = cp; nm = cm;
;             bf16x8 qr[8];
;             at_unit_prologue(wl, qr, cq, ck, cv, ctq, cdl, lna);
.LBB0_364:
	s_ashr_i32 s8, s86, 8
	s_ashr_i32 s9, s8, 31
	s_and_b32 s18, s8, 7
	s_lshl_b64 s[14:15], s[8:9], 19
	s_lshl_b64 s[16:17], s[8:9], 20
	s_add_u32 s12, s84, s16
	s_addc_u32 s13, s85, s17
	s_add_u32 s38, s94, 0x10400000
	s_addc_u32 s49, s95, 0
	s_add_u32 s54, s38, s14
	s_addc_u32 s55, s49, s15
	s_add_u32 s51, s94, 0x12400000
	s_addc_u32 s52, s95, 0
	s_add_u32 s56, s51, s14
	s_addc_u32 s57, s52, s15
	s_add_i32 s18, s18, 1
	v_cvt_f32_ubyte0_e32 v0, s18
	s_mov_b32 s53, 0x42fc0000
	v_mov_b32_e32 v133, 0x42800000
	v_cmp_lt_f32_e32 vcc, s53, v0
	s_and_b64 s[14:15], vcc, exec
	s_cselect_b32 s14, 0xffffffc0, 0
	v_cndmask_b32_e32 v1, 0, v133, vcc
	v_sub_f32_e32 v0, v1, v0
	v_exp_f32_e32 v0, v0
	v_readlane_b32 s20, v254, 2
	v_readlane_b32 s22, v254, 4
	v_readlane_b32 s23, v254, 5
	v_ldexp_f32 v0, v0, s14
	v_mul_f32_e32 v0, 0x3fb8aa3b, v0
	s_add_u32 s14, s22, s6
	v_cvt_f32_ubyte0_e32 v1, s88
	s_addc_u32 s15, s23, s7
	s_and_b32 s6, s86, s11
	v_mul_f32_e32 v128, v0, v1
	v_mov_b32_e32 v0, v131
	s_or_b32 s92, s10, s6
	s_lshl_b64 s[6:7], s[8:9], 15
	s_add_u32 s44, s14, s6
	v_ashrrev_i32_e32 v1, 3, v0
	v_bitop3_b32 v0, v0, v1, 7 bitop3:0x6c
	v_subrev_u32_e32 v1, 64, v1
	s_addc_u32 s45, s15, s7
	v_mul_lo_u32 v1, v1, s88
	s_add_u32 s16, s4, s16
	v_add_u32_e32 v1, s92, v1
	v_mov_b32_e32 v172, 0xfff
	s_addc_u32 s17, s5, s17
	v_lshlrev_b32_e32 v0, 4, v0
	v_med3_i32 v2, v1, 0, v172
	s_lshl_b32 s4, s88, 3
	s_mov_b32 m0, s83
	v_lshl_add_u32 v2, v2, 7, v0
	v_add_u32_e32 v1, s4, v1
	global_load_lds_dwordx4 v2, s[54:55]
	v_med3_i32 v2, v1, 0, v172
	s_add_i32 s76, s83, 0x400
	v_lshl_add_u32 v2, v2, 7, v0
	s_mov_b32 m0, s76
	v_add_u32_e32 v1, s4, v1
	global_load_lds_dwordx4 v2, s[54:55]
	v_med3_i32 v2, v1, 0, v172
	s_add_i32 s77, s83, 0x800
	v_add_u32_e32 v1, s4, v1
	v_lshl_add_u32 v2, v2, 7, v0
	s_mov_b32 m0, s77
	v_med3_i32 v1, v1, 0, v172
	s_add_i32 s78, s83, 0xc00
	global_load_lds_dwordx4 v2, s[54:55]
	v_lshl_add_u32 v0, v1, 7, v0
	s_mov_b32 m0, s78
	s_add_i32 s79, s83, 0x2000
	global_load_lds_dwordx4 v0, s[54:55]
	v_mov_b32_e32 v0, v131
	s_mov_b32 m0, s79
	v_ashrrev_i32_e32 v1, 3, v0
	v_bitop3_b32 v0, v0, v1, 7 bitop3:0x6c
	v_subrev_u32_e32 v1, 64, v1
	v_mul_lo_u32 v1, v1, s88
	v_add_u32_e32 v1, s92, v1
	v_lshlrev_b32_e32 v0, 4, v0
	v_med3_i32 v2, v1, 0, v172
	v_lshl_add_u32 v2, v2, 7, v0
	v_add_u32_e32 v1, s4, v1
	global_load_lds_dwordx4 v2, s[56:57]
	v_med3_i32 v2, v1, 0, v172
	s_add_i32 s80, s83, 0x2400
	v_lshl_add_u32 v2, v2, 7, v0
	s_mov_b32 m0, s80
	v_add_u32_e32 v1, s4, v1
	global_load_lds_dwordx4 v2, s[56:57]
	v_med3_i32 v2, v1, 0, v172
	s_add_i32 s81, s83, 0x2800
	v_add_u32_e32 v1, s4, v1
	v_lshl_add_u32 v2, v2, 7, v0
	s_mov_b32 m0, s81
	v_med3_i32 v1, v1, 0, v172
	s_add_i32 s82, s83, 0x2c00
	global_load_lds_dwordx4 v2, s[56:57]
	v_lshl_add_u32 v0, v1, 7, v0
	s_mov_b32 m0, s82
	v_and_b32_e32 v173, 31, v131
	global_load_lds_dwordx4 v0, s[56:57]
	v_mul_u32_u24_e32 v0, s88, v173
	v_ashrrev_i32_e32 v2, 2, v131
	v_add_lshl_u32 v112, v0, s92, 8
	v_mov_b32_e32 v113, 0
	v_and_b32_e32 v114, -8, v2
	v_lshl_add_u64 v[0:1], s[12:13], 0, v[112:113]
	v_ashrrev_i32_e32 v115, 31, v114
	v_lshl_add_u64 v[0:1], v[114:115], 1, v[0:1]
	global_load_dwordx4 v[80:83], v[0:1], off
	global_load_dwordx4 v[84:87], v[0:1], off offset:32
	global_load_dwordx4 v[88:91], v[0:1], off offset:64
	global_load_dwordx4 v[92:95], v[0:1], off offset:96
	global_load_dwordx4 v[96:99], v[0:1], off offset:128
	global_load_dwordx4 v[100:103], v[0:1], off offset:160
	global_load_dwordx4 v[104:107], v[0:1], off offset:192
	global_load_dwordx4 v[108:111], v[0:1], off offset:224
	v_ashrrev_i32_e32 v0, 5, v131
	v_lshlrev_b32_e32 v2, 3, v0
	v_lshlrev_b32_e32 v0, 2, v0
	v_sub_u32_e32 v0, v0, v173
	v_subrev_u32_e32 v175, 64, v0
	v_lshlrev_b32_e32 v0, 8, v173
	v_lshlrev_b32_e32 v3, 4, v131
	s_movk_i32 s6, 0x70
	v_add3_u32 v176, s83, v0, v2
	v_mov_b32_e32 v0, 0xf0
; #define GAS __attribute__((address_space(1)))
; #define LAS __attribute__((address_space(3)))
; __device__ __forceinline__ void attn_unit(const bool FINAL, const bool HN, LAS unsigned char* wl, const bf16_t* qb, const bf16_t* kb, const bf16_t* vb, int tq0, int dil, float sl, bf16x8 (&qr)[8], const bf16_t* nqb, const bf16_t* nkb, const bf16_t* nvb, int ntq0, int ndil, ...
;     const int r32 = lane & 31, hi = lane >> 5;
;     LAS unsigned char* kbuf = wl; LAS unsigned char* vbuf = wl + 8192;
;     const int jlo = 64 - tq0 / dil, jhi = 64 + (SEQ - 1 - tq0) / dil;
;     const float lo_i = (float)max(-64, jlo - 64 - r32), hi_i = (float)min(64, jhi - 64 - r32);
;     const bool interior = (jlo <= 0) && (jhi >= 159);
;     float m_run = -1e30f, l_run = 0.f;
;     f32x16 oT[4];
; #pragma unroll
;     for (int d0 = 0; d0 < 4; ++d0)
; #pragma unroll
;         for (int r = 0; r < 16; ++r) oT[d0][r] = 0.f;
;     asm volatile("s_waitcnt vmcnt(0)" ::: "memory");
; #pragma unroll
;     for (int s = 0; s < 8; ++s) asm volatile("" : "+v"(qr[s]));
;     long q8[8];
; #pragma unroll
;     for (int s = 0; s < 8; ++s) q8[s] = bf16x8_to_fp8(qr[s]);
;     f32x2 st1 = {0.f, 0.f}, st2 = {0.f, 0.f};
;     if (FINAL) { const size_t tqs = (size_t)(tq0 + dil * r32) * 2; st1 = *(const GAS f32x2*)(ml0 + tqs); st2 = *(const GAS f32x2*)(ml1 + tqs); }
;     const int rr0 = lane >> 4, cs = lane & 15;
;     const LAS unsigned char* krd = kbuf + r32 * 128 + hi * 8;
;     const int kx = (r32 & 7) << 4;
; #pragma unroll 1
	v_bitop3_b32 v16, v3, s6, v3 bitop3:0xc
	v_bitop3_b32 v23, v3, s6, v0 bitop3:0x6c
	s_movk_i32 s6, 0x80
	v_bitop3_b32 v24, v3, s6, v0 bitop3:0x6c
	s_movk_i32 s6, 0x90
	v_bitop3_b32 v25, v3, s6, v0 bitop3:0x6c
	s_movk_i32 s6, 0xa0
	v_bitop3_b32 v26, v3, s6, v0 bitop3:0x6c
	s_movk_i32 s6, 0xb0
	v_bitop3_b32 v27, v3, s6, v0 bitop3:0x6c
	s_movk_i32 s6, 0xc0
	v_ashrrev_i32_e32 v174, 4, v131
	v_lshlrev_b32_e32 v1, 7, v173
	v_mov_b32_e32 v4, 0x70
	s_movk_i32 s7, 0x50
	s_movk_i32 s8, 0x60
	v_bitop3_b32 v28, v3, s6, v0 bitop3:0x6c
	s_movk_i32 s6, 0xd0
	v_add3_u32 v1, s83, v1, v2
	v_bitop3_b32 v7, v3, 16, v4 bitop3:0x6c
	v_bitop3_b32 v9, v3, 32, v4 bitop3:0x6c
	v_bitop3_b32 v11, v3, 48, v4 bitop3:0x6c
	v_bitop3_b32 v13, v3, 64, v4 bitop3:0x6c
	v_bitop3_b32 v14, v3, s7, v4 bitop3:0x6c
	v_bitop3_b32 v15, v3, s8, v4 bitop3:0x6c
	v_bitop3_b32 v29, v3, s6, v0 bitop3:0x6c
	s_movk_i32 s6, 0xe0
	v_add_u32_e32 v2, 4, v174
	v_add_u32_e32 v4, 8, v174
	v_add_u32_e32 v6, 12, v174
	v_add_u32_e32 v8, 20, v174
	v_add_u32_e32 v10, 24, v174
	v_add_u32_e32 v12, 28, v174
	v_bitop3_b32 v17, v3, 16, v0 bitop3:0x6c
	v_bitop3_b32 v18, v3, 32, v0 bitop3:0x6c
	v_bitop3_b32 v19, v3, 48, v0 bitop3:0x6c
	v_bitop3_b32 v20, v3, 64, v0 bitop3:0x6c
	v_bitop3_b32 v21, v3, s7, v0 bitop3:0x6c
	v_bitop3_b32 v22, v3, s8, v0 bitop3:0x6c
	v_bitop3_b32 v30, v3, s6, v0 bitop3:0x6c
	v_xor_b32_e32 v0, v174, v131
	v_xor_b32_e32 v2, v2, v131
	v_xor_b32_e32 v4, v4, v131
	v_xor_b32_e32 v6, v6, v131
	v_xor_b32_e32 v8, v8, v131
	v_xor_b32_e32 v10, v10, v131
	v_xor_b32_e32 v12, v12, v131
	v_readlane_b32 s21, v254, 3
	s_movk_i32 s9, 0xf0
	v_lshlrev_b32_e32 v0, 3, v0
	v_lshlrev_b32_e32 v2, 3, v2
	v_lshlrev_b32_e32 v4, 3, v4
	v_lshlrev_b32_e32 v6, 3, v6
	v_lshlrev_b32_e32 v8, 3, v8
	v_lshlrev_b32_e32 v10, 3, v10
	v_lshlrev_b32_e32 v12, 3, v12
	v_and_b32_e32 v5, 0x70, v3
	v_and_b32_e32 v177, 0xf0, v3
	v_bitop3_b32 v3, v3, s9, v3 bitop3:0xc
	v_lshl_add_u32 v31, v174, 8, s83
	v_and_b32_e32 v0, 0x78, v0
	v_and_b32_e32 v2, 0x78, v2
	v_and_b32_e32 v4, 0x78, v4
	v_and_b32_e32 v6, 0x78, v6
	v_and_b32_e32 v8, 0x78, v8
	v_and_b32_e32 v10, 0x78, v10
	v_and_b32_e32 v12, 0x78, v12
	s_mov_b32 s18, 0x41200000
	s_mov_b32 s20, 0x41800000
	s_mov_b32 s22, 0x41900000
	s_mov_b32 s24, 0x41c00000
	s_mov_b32 s26, 0x41d00000
	s_mov_b32 s28, 0x42000000
	s_mov_b32 s30, 0x42080000
	s_mov_b32 s66, 0x42800000
	s_mov_b32 s67, 0
	v_cmp_gt_u32_e64 s[4:5], 32, v131
	s_and_b32 s87, s86, 3
	v_add_u32_e32 v178, v1, v5
	v_add_u32_e32 v179, v1, v7
	v_add_u32_e32 v180, v1, v9
	v_add_u32_e32 v181, v1, v11
	v_add_u32_e32 v182, v1, v13
	v_add_u32_e32 v183, v1, v14
	v_add_u32_e32 v184, v1, v15
	v_add_u32_e32 v185, v1, v16
	s_mov_b32 s89, 0xf149f2ca
	s_mov_b32 s19, 0x41300000
	s_mov_b32 s21, 0x41880000
	s_mov_b32 s23, 0x41980000
	s_mov_b32 s25, 0x41c80000
	s_mov_b32 s27, 0x41d80000
	s_mov_b32 s29, 0x42040000
	s_mov_b32 s31, 0x420c0000
	s_mov_b32 s90, 0xc2800000
	v_add_u32_e32 v186, v176, v17
	v_add_u32_e32 v187, v176, v18
	v_add_u32_e32 v188, v176, v19
	v_add_u32_e32 v189, v176, v20
	v_add_u32_e32 v190, v176, v21
	v_add_u32_e32 v191, v176, v22
	v_add_u32_e32 v192, v176, v23
	v_add_u32_e32 v193, v176, v24
	v_add_u32_e32 v194, v176, v25
	v_add_u32_e32 v195, v176, v26
	v_add_u32_e32 v196, v176, v27
	v_add_u32_e32 v197, v176, v28
	v_add_u32_e32 v198, v176, v29
	v_add_u32_e32 v199, v176, v30
	v_add_u32_e32 v200, v176, v3
	v_add_u32_e32 v201, v31, v177
	v_lshlrev_b32_e32 v112, 1, v0
	v_lshlrev_b32_e32 v116, 1, v2
	v_lshlrev_b32_e32 v118, 1, v4
	v_lshlrev_b32_e32 v120, 1, v6
	v_lshlrev_b32_e32 v122, 1, v8
	v_lshlrev_b32_e32 v124, 1, v10
	v_lshlrev_b32_e32 v126, 1, v12
	v_mov_b32_e32 v202, 0xf149f2ca
	v_mov_b32_e32 v203, v113
	s_mov_b32 s91, s86
	s_mov_b64 s[34:35], s[54:55]
	s_mov_b64 s[36:37], s[56:57]
	s_mov_b64 s[42:43], s[16:17]
	s_mov_b64 s[40:41], s[44:45]
	s_waitcnt vmcnt(0)
	s_branch .LBB0_366

; #define LAS __attribute__((address_space(3)))
; __device__ __forceinline__ void attn_unit(const bool FINAL, const bool HN, LAS unsigned char* wl, const bf16_t* qb, const bf16_t* kb, const bf16_t* vb, int tq0, int dil, float sl, bf16x8 (&qr)[8], const bf16_t* nqb, const bf16_t* nkb, const bf16_t* nvb, int ntq0, int ndil, ...
;     const int r32 = lane & 31, hi = lane >> 5;
;     LAS unsigned char* kbuf = wl; LAS unsigned char* vbuf = wl + 8192;
;     const int jlo = 64 - tq0 / dil, jhi = 64 + (SEQ - 1 - tq0) / dil;
;     const float lo_i = (float)max(-64, jlo - 64 - r32), hi_i = (float)min(64, jhi - 64 - r32);
;     const bool interior = (jlo <= 0) && (jhi >= 159);
;     float m_run = -1e30f, l_run = 0.f;
;     f32x16 oT[4];
; #pragma unroll
;     for (int d0 = 0; d0 < 4; ++d0)
; #pragma unroll
;         for (int r = 0; r < 16; ++r) oT[d0][r] = 0.f;
;     asm volatile("s_waitcnt vmcnt(0)" ::: "memory");
; #pragma unroll
;     for (int s = 0; s < 8; ++s) asm volatile("" : "+v"(qr[s]));
;     long q8[8];
; #pragma unroll
;     for (int s = 0; s < 8; ++s) q8[s] = bf16x8_to_fp8(qr[s]);
;     f32x2 st1 = {0.f, 0.f}, st2 = {0.f, 0.f};
.LBB0_373:
	s_and_b32 s6, s88, 0xffff
	v_cvt_f32_u32_e32 v0, s6
	s_and_b32 s6, s92, 0xffff
	v_cvt_f32_u32_e32 v1, s6
	s_waitcnt vmcnt(13)
	v_rcp_iflag_f32_e32 v2, v0
	s_waitcnt vmcnt(13)
	v_mov_b32_e32 v134, v113
	v_mov_b32_e32 v135, v113
	v_mul_f32_e32 v3, v1, v2
	v_trunc_f32_e32 v3, v3
	v_cvt_u32_f32_e32 v4, v3
	v_fma_f32 v1, -v3, v0, v1
	v_cmp_ge_f32_e64 s[6:7], |v1|, v0
	s_cmp_lg_u64 s[6:7], 0
	v_readfirstlane_b32 s6, v4
	s_addc_u32 s6, s6, 0
	s_xor_b32 s7, s92, 0xfff
	s_and_b32 s8, s6, 0xffff
	s_and_b32 s6, s7, 0xffff
	v_cvt_f32_u32_e32 v1, s6
	v_add_u32_e32 v3, s8, v173
	v_sub_u32_e32 v3, 0, v3
	v_max_i32_e32 v3, 0xffffffc0, v3
	v_mul_f32_e32 v2, v1, v2
	v_trunc_f32_e32 v2, v2
	v_cvt_u32_f32_e32 v4, v2
	v_fma_f32 v1, -v2, v0, v1
	v_cmp_ge_f32_e64 s[6:7], |v1|, v0
	s_cmp_lg_u64 s[6:7], 0
	v_readfirstlane_b32 s6, v4
	s_addc_u32 s6, s6, 0
	s_and_b32 s6, s6, 0xffff
	v_sub_u32_e32 v0, s6, v173
	v_min_i32_e32 v0, 64, v0
	v_cvt_f32_i32_e32 v130, v0
	v_lshlrev_b32_e32 v0, 16, v80
	v_and_b32_e32 v1, 0xffff0000, v80
	v_cvt_f32_i32_e32 v132, v3
	v_cvt_pk_fp8_f32 v134, v0, v1
	v_lshlrev_b32_e32 v2, 16, v82
	v_and_b32_e32 v3, 0xffff0000, v82
	v_cvt_pk_fp8_f32 v135, v2, v3
	v_lshlrev_b32_e32 v0, 16, v81
	v_and_b32_e32 v1, 0xffff0000, v81
	v_cvt_pk_fp8_f32 v134, v0, v1 op_sel:[0,0,1]
	v_lshlrev_b32_e32 v0, 16, v83
	v_and_b32_e32 v1, 0xffff0000, v83
	v_cvt_pk_fp8_f32 v135, v0, v1 op_sel:[0,0,1]
	v_lshlrev_b32_e32 v0, 16, v84
	v_and_b32_e32 v1, 0xffff0000, v84
	v_mov_b32_e32 v136, v113
	v_cvt_pk_fp8_f32 v136, v0, v1
	v_lshlrev_b32_e32 v2, 16, v86
	v_and_b32_e32 v3, 0xffff0000, v86
	v_mov_b32_e32 v137, v113
	v_cvt_pk_fp8_f32 v137, v2, v3
	v_lshlrev_b32_e32 v0, 16, v85
	v_and_b32_e32 v1, 0xffff0000, v85
	v_cvt_pk_fp8_f32 v136, v0, v1 op_sel:[0,0,1]
	v_lshlrev_b32_e32 v0, 16, v87
	v_and_b32_e32 v1, 0xffff0000, v87
	v_cvt_pk_fp8_f32 v137, v0, v1 op_sel:[0,0,1]
	v_lshlrev_b32_e32 v0, 16, v88
	v_and_b32_e32 v1, 0xffff0000, v88
	v_mov_b32_e32 v138, v113
	v_cvt_pk_fp8_f32 v138, v0, v1
	v_lshlrev_b32_e32 v2, 16, v90
	v_and_b32_e32 v3, 0xffff0000, v90
	v_mov_b32_e32 v139, v113
	v_cvt_pk_fp8_f32 v139, v2, v3
	v_lshlrev_b32_e32 v0, 16, v89
	v_and_b32_e32 v1, 0xffff0000, v89
	v_cvt_pk_fp8_f32 v138, v0, v1 op_sel:[0,0,1]
	v_lshlrev_b32_e32 v0, 16, v91
	v_and_b32_e32 v1, 0xffff0000, v91
	v_cvt_pk_fp8_f32 v139, v0, v1 op_sel:[0,0,1]
	v_lshlrev_b32_e32 v0, 16, v92
	v_and_b32_e32 v1, 0xffff0000, v92
	v_mov_b32_e32 v140, v113
	v_cvt_pk_fp8_f32 v140, v0, v1
	v_lshlrev_b32_e32 v2, 16, v94
	v_and_b32_e32 v3, 0xffff0000, v94
	v_mov_b32_e32 v141, v113
	v_cvt_pk_fp8_f32 v141, v2, v3
	v_lshlrev_b32_e32 v0, 16, v93
	v_and_b32_e32 v1, 0xffff0000, v93
	v_cvt_pk_fp8_f32 v140, v0, v1 op_sel:[0,0,1]
	v_lshlrev_b32_e32 v0, 16, v95
	v_and_b32_e32 v1, 0xffff0000, v95
	v_cvt_pk_fp8_f32 v141, v0, v1 op_sel:[0,0,1]
	v_lshlrev_b32_e32 v0, 16, v96
	v_and_b32_e32 v1, 0xffff0000, v96
	v_mov_b32_e32 v142, v113
	v_cvt_pk_fp8_f32 v142, v0, v1
	v_lshlrev_b32_e32 v2, 16, v98
	v_and_b32_e32 v3, 0xffff0000, v98
	v_mov_b32_e32 v143, v113
	v_cvt_pk_fp8_f32 v143, v2, v3
	v_lshlrev_b32_e32 v0, 16, v97
	v_and_b32_e32 v1, 0xffff0000, v97
	v_cvt_pk_fp8_f32 v142, v0, v1 op_sel:[0,0,1]
	v_lshlrev_b32_e32 v0, 16, v99
	v_and_b32_e32 v1, 0xffff0000, v99
	v_cvt_pk_fp8_f32 v143, v0, v1 op_sel:[0,0,1]
	v_lshlrev_b32_e32 v0, 16, v100
	v_and_b32_e32 v1, 0xffff0000, v100
	v_mov_b32_e32 v144, v113
	v_cvt_pk_fp8_f32 v144, v0, v1
	v_lshlrev_b32_e32 v2, 16, v102
	v_and_b32_e32 v3, 0xffff0000, v102
	v_mov_b32_e32 v145, v113
	v_cvt_pk_fp8_f32 v145, v2, v3
	v_lshlrev_b32_e32 v0, 16, v101
	v_and_b32_e32 v1, 0xffff0000, v101
	v_cvt_pk_fp8_f32 v144, v0, v1 op_sel:[0,0,1]
	v_lshlrev_b32_e32 v0, 16, v103
	v_and_b32_e32 v1, 0xffff0000, v103
	v_cvt_pk_fp8_f32 v145, v0, v1 op_sel:[0,0,1]
	v_lshlrev_b32_e32 v0, 16, v104
	v_and_b32_e32 v1, 0xffff0000, v104
	v_mov_b32_e32 v146, v113
	v_cvt_pk_fp8_f32 v146, v0, v1
	v_lshlrev_b32_e32 v2, 16, v106
	v_and_b32_e32 v3, 0xffff0000, v106
	v_mov_b32_e32 v147, v113
	v_cvt_pk_fp8_f32 v147, v2, v3
	v_lshlrev_b32_e32 v0, 16, v105
	v_and_b32_e32 v1, 0xffff0000, v105
	v_cvt_pk_fp8_f32 v146, v0, v1 op_sel:[0,0,1]
	v_lshlrev_b32_e32 v0, 16, v107
	v_and_b32_e32 v1, 0xffff0000, v107
	v_cvt_pk_fp8_f32 v147, v0, v1 op_sel:[0,0,1]
	v_lshlrev_b32_e32 v0, 16, v108
	v_and_b32_e32 v1, 0xffff0000, v108
	v_mov_b32_e32 v148, v113
	v_cvt_pk_fp8_f32 v148, v0, v1
	v_lshlrev_b32_e32 v2, 16, v110
	v_and_b32_e32 v3, 0xffff0000, v110
	v_mov_b32_e32 v149, v113
	v_cvt_pk_fp8_f32 v149, v2, v3
	v_lshlrev_b32_e32 v0, 16, v109
	v_and_b32_e32 v1, 0xffff0000, v109
	s_cmpk_gt_u32 s6, 0x5e
	v_cvt_pk_fp8_f32 v148, v0, v1 op_sel:[0,0,1]
	v_lshlrev_b32_e32 v0, 16, v111
	v_and_b32_e32 v1, 0xffff0000, v111
	s_cselect_b64 s[6:7], -1, 0
	s_cmp_gt_u32 s8, 63
	v_cvt_pk_fp8_f32 v149, v0, v1 op_sel:[0,0,1]
	s_cselect_b64 s[8:9], -1, 0
	v_mov_b32_e32 v48, v113
	v_mov_b32_e32 v49, v113
	s_and_b64 s[58:59], s[8:9], s[6:7]
	v_xor_b32_e32 v150, 0x80000000, v128
	v_mov_b32_e32 v50, v113
	v_mov_b32_e32 v51, v113
	v_mov_b32_e32 v52, v113
	v_mov_b32_e32 v53, v113
	v_mov_b32_e32 v54, v113
	v_mov_b32_e32 v55, v113
	v_mov_b32_e32 v56, v113
	v_mov_b32_e32 v57, v113
	v_mov_b32_e32 v58, v113
	v_mov_b32_e32 v59, v113
	v_mov_b32_e32 v60, v113
	v_mov_b32_e32 v61, v113
	v_mov_b32_e32 v62, v113
	v_mov_b32_e32 v63, v113
	v_mov_b64_e32 v[32:33], v[48:49]
	v_mov_b64_e32 v[16:17], v[48:49]
	v_mov_b64_e32 v[0:1], v[48:49]
	s_xor_b64 s[60:61], s[58:59], -1
	s_lshl_b32 s14, s88, 11
	v_mov_b32_e32 v129, v128
	v_mov_b32_e32 v151, v150
	v_mov_b32_e32 v117, v132
	v_mov_b32_e32 v119, v130
	s_mov_b32 s15, 0
	v_mov_b32_e32 v205, 0xf149f2ca
	v_mov_b32_e32 v121, 0
	v_mov_b64_e32 v[34:35], v[50:51]
	v_mov_b64_e32 v[36:37], v[52:53]
	v_mov_b64_e32 v[38:39], v[54:55]
	v_mov_b64_e32 v[40:41], v[56:57]
	v_mov_b64_e32 v[42:43], v[58:59]
	v_mov_b64_e32 v[44:45], v[60:61]
	v_mov_b64_e32 v[46:47], v[62:63]
	v_mov_b64_e32 v[18:19], v[50:51]
	v_mov_b64_e32 v[20:21], v[52:53]
	v_mov_b64_e32 v[22:23], v[54:55]
	v_mov_b64_e32 v[24:25], v[56:57]
	v_mov_b64_e32 v[26:27], v[58:59]
	v_mov_b64_e32 v[28:29], v[60:61]
	v_mov_b64_e32 v[30:31], v[62:63]
	v_mov_b64_e32 v[2:3], v[50:51]
	v_mov_b64_e32 v[4:5], v[52:53]
	v_mov_b64_e32 v[6:7], v[54:55]
	v_mov_b64_e32 v[8:9], v[56:57]
	v_mov_b64_e32 v[10:11], v[58:59]
	v_mov_b64_e32 v[12:13], v[60:61]
	v_mov_b64_e32 v[14:15], v[62:63]
	s_mov_b32 s93, 0
	s_cmp_lg_u32 s15, 0
	s_cselect_b64 s[74:75], -1, 0
	s_cmp_eq_u32 s15, 0
	s_cbranch_scc1 .LBB0_375

; __device__ __forceinline__ unsigned lane_id_fresh() { unsigned m = ~0u; asm volatile("" : "+s"(m)); return __builtin_amdgcn_mbcnt_hi(m, __builtin_amdgcn_mbcnt_lo(m, 0u)); }
; #define LAS __attribute__((address_space(3)))
; __global__ void __launch_bounds__(NWAVES * 64, 2) mk_fwd(Args args) {
;     ...
;         LAS unsigned char* wl = lds + wave * 16384;
;         int lna = (int)lane_id_fresh(); asm volatile("" : "+v"(lna));
;         constexpr int NU = NB * NH * 128;
;     ...
;         int U = vwave;
;         if (U < NU) {
;             const bf16_t *cq, *ck, *cv, *nq, *nk, *nv, *c0, *c1, *n0, *n1; const float *cm0, *cm1, *nm0, *nm1; bf16_t *cy, *ny; int ctq, ntq = 0; float csl, nsl = 0.f;
;             AT_DEC_C(U, cq, ck, cv, ctq, csl, c0, c1, cm0, cm1, cy);
;             nq = cq; nk = ck; nv = cv; n0 = c0; n1 = c1; nm0 = cm0; nm1 = cm1; ny = cy;
;             bf16x8 qr[8];
;             at_unit_prologue(wl, qr, cq, ck, cv, ctq, 1, lna);
.LBB0_471:
	v_writelane_b32 v254, s94, 28
	s_mov_b32 s4, -1
	s_waitcnt lgkmcnt(0)
	v_writelane_b32 v254, s95, 29
	s_barrier
	v_writelane_b32 v254, s96, 30
	v_mbcnt_lo_u32_b32 v0, s4, 0
	v_mbcnt_hi_u32_b32 v198, s4, v0
	s_cmpk_gt_i32 s86, 0xfff
	v_writelane_b32 v254, s97, 31
	s_cbranch_scc1 .LBB0_518
	v_readlane_b32 s16, v254, 2
	v_readlane_b32 s18, v254, 4
	v_readlane_b32 s19, v254, 5
	s_add_u32 s16, s18, 0x4000000
	s_addc_u32 s52, s19, 0
	s_add_u32 s53, s18, 0x4100000
	s_addc_u32 s87, s19, 0
	s_ashr_i32 s4, s86, 7
	s_and_b32 s12, s4, 7
	s_ashr_i32 s5, s4, 31
	s_ashr_i32 s13, s86, 10
	s_lshl_b32 s15, s12, 7
	s_lshl_b64 s[6:7], s[4:5], 19
	s_lshl_b64 s[8:9], s[4:5], 20
	s_add_u32 s10, s84, s8
	s_addc_u32 s11, s85, s9
	s_add_u32 s88, s94, 0x10400000
	s_addc_u32 s89, s95, 0
	s_add_u32 s60, s88, s6
	s_addc_u32 s61, s89, s7
	s_add_u32 s90, s94, 0x12400000
	s_addc_u32 s91, s95, 0
	s_add_u32 s70, s90, s6
	s_addc_u32 s71, s91, s7
	s_add_i32 s12, s12, 1
	v_cvt_f32_ubyte0_e32 v0, s12
	s_mov_b32 s6, 0x42fc0000
	v_mov_b32_e32 v1, 0x42800000
	v_cmp_lt_f32_e32 vcc, s6, v0
	s_and_b64 s[6:7], vcc, exec
	s_cselect_b32 s6, 0xffffffc0, 0
	v_cndmask_b32_e32 v1, 0, v1, vcc
	v_sub_f32_e32 v0, v1, v0
	v_exp_f32_e32 v0, v0
	s_mov_b32 m0, s83
	v_and_b32_e32 v200, 31, v198
	v_ashrrev_i32_e32 v201, 4, v198
	v_ldexp_f32 v0, v0, s6
	s_lshl_b32 s6, s86, 5
	s_and_b32 s94, s6, 0xfe0
	s_add_u32 s58, s18, s8
	s_addc_u32 s59, s19, s9
	s_add_u32 s56, s0, s8
	s_addc_u32 s57, s1, s9
	s_lshl_b64 s[6:7], s[4:5], 15
	v_mul_f32_e32 v114, 0x3fb8aa3b, v0
	s_add_u32 s4, s16, s6
	v_mov_b32_e32 v0, v198
	s_addc_u32 s5, s52, s7
	s_add_u32 s6, s53, s6
	v_ashrrev_i32_e32 v1, 3, v0
	v_bitop3_b32 v0, v0, v1, 7 bitop3:0x6c
	v_add_u32_e32 v1, s94, v1
	s_addc_u32 s7, s87, s7
	s_mul_hi_i32 s8, s13, 0xc00000
	s_mul_i32 s13, s13, 0xc00000
	v_max_i32_e32 v2, 64, v1
	s_add_u32 s9, s68, s13
	v_subrev_u32_e32 v2, 64, v2
	s_addc_u32 s8, s69, s8
	v_lshlrev_b32_e32 v0, 4, v0
	v_min_u32_e32 v2, 0xfff, v2
	s_add_u32 s9, s9, s15
	v_lshl_add_u32 v2, v2, 7, v0
	s_addc_u32 s8, s8, 0
	global_load_lds_dwordx4 v2, s[60:61]
	v_max_i32_e32 v2, 56, v1
	s_add_u32 s54, s9, 0x800
	v_subrev_u32_e32 v2, 56, v2
	s_addc_u32 s55, s8, 0
	v_min_u32_e32 v2, 0xfff, v2
	s_add_i32 s95, s83, 0x400
	v_lshl_add_u32 v2, v2, 7, v0
	s_mov_b32 m0, s95
	s_add_i32 s96, s83, 0x800
	global_load_lds_dwordx4 v2, s[60:61]
	v_max_i32_e32 v2, 48, v1
	v_subrev_u32_e32 v2, 48, v2
	v_max_i32_e32 v1, 40, v1
	v_min_u32_e32 v2, 0xfff, v2
	v_subrev_u32_e32 v1, 40, v1
	v_lshl_add_u32 v2, v2, 7, v0
	s_mov_b32 m0, s96
	v_min_u32_e32 v1, 0xfff, v1
	s_add_i32 s38, s83, 0xc00
	global_load_lds_dwordx4 v2, s[60:61]
	v_lshl_add_u32 v0, v1, 7, v0
	s_mov_b32 m0, s38
	s_add_i32 s39, s83, 0x2000
	global_load_lds_dwordx4 v0, s[60:61]
	v_mov_b32_e32 v0, v198
	s_mov_b32 m0, s39
	v_ashrrev_i32_e32 v1, 3, v0
	v_bitop3_b32 v0, v0, v1, 7 bitop3:0x6c
	v_add_u32_e32 v1, s94, v1
	v_max_i32_e32 v2, 64, v1
	v_subrev_u32_e32 v2, 64, v2
	v_lshlrev_b32_e32 v0, 4, v0
	v_min_u32_e32 v2, 0xfff, v2
	v_lshl_add_u32 v2, v2, 7, v0
	global_load_lds_dwordx4 v2, s[70:71]
	v_max_i32_e32 v2, 56, v1
	v_subrev_u32_e32 v2, 56, v2
	v_min_u32_e32 v2, 0xfff, v2
	s_add_i32 s67, s83, 0x2400
	v_lshl_add_u32 v2, v2, 7, v0
	s_mov_b32 m0, s67
	s_add_i32 s82, s83, 0x2800
	global_load_lds_dwordx4 v2, s[70:71]
	v_max_i32_e32 v2, 48, v1
	v_subrev_u32_e32 v2, 48, v2
	v_max_i32_e32 v1, 40, v1
	v_min_u32_e32 v2, 0xfff, v2
	v_subrev_u32_e32 v1, 40, v1
	v_lshl_add_u32 v2, v2, 7, v0
	s_mov_b32 m0, s82
	v_min_u32_e32 v1, 0xfff, v1
	s_add_i32 s66, s83, 0x2c00
	global_load_lds_dwordx4 v2, s[70:71]
	v_lshl_add_u32 v0, v1, 7, v0
	s_mov_b32 m0, s66
	v_mov_b32_e32 v1, 0
	global_load_lds_dwordx4 v0, s[70:71]
	v_or_b32_e32 v0, s94, v200
	v_lshlrev_b32_e32 v0, 8, v0
	v_lshl_add_u64 v[2:3], s[10:11], 0, v[0:1]
	v_ashrrev_i32_e32 v0, 2, v198
	v_and_b32_e32 v162, -8, v0
	v_ashrrev_i32_e32 v163, 31, v162
	v_lshl_add_u64 v[2:3], v[162:163], 1, v[2:3]
	global_load_dwordx4 v[82:85], v[2:3], off
	global_load_dwordx4 v[86:89], v[2:3], off offset:32
	global_load_dwordx4 v[90:93], v[2:3], off offset:64
	global_load_dwordx4 v[94:97], v[2:3], off offset:96
	global_load_dwordx4 v[98:101], v[2:3], off offset:128
	global_load_dwordx4 v[102:105], v[2:3], off offset:160
	global_load_dwordx4 v[106:109], v[2:3], off offset:192
	global_load_dwordx4 v[110:113], v[2:3], off offset:224
	v_ashrrev_i32_e32 v0, 5, v198
	v_lshlrev_b32_e32 v3, 3, v0
	v_lshlrev_b32_e32 v0, 2, v0
	v_sub_u32_e32 v0, v0, v200
	v_subrev_u32_e32 v202, 64, v0
	v_xor_b32_e32 v0, v201, v198
	v_lshlrev_b32_e32 v0, 3, v0
	v_add_u32_e32 v29, 4, v201
	v_and_b32_e32 v164, 0x78, v0
	v_xor_b32_e32 v0, v29, v198
	v_lshlrev_b32_e32 v0, 3, v0
	v_add_u32_e32 v199, 8, v201
	v_and_b32_e32 v166, 0x78, v0
	v_xor_b32_e32 v0, v199, v198
	v_lshlrev_b32_e32 v0, 3, v0
	v_add_u32_e32 v203, 12, v201
	v_and_b32_e32 v168, 0x78, v0
; #define GAS __attribute__((address_space(1)))
; #define LAS __attribute__((address_space(3)))
; __device__ __forceinline__ void attn_unit(const bool FINAL, const bool HN, LAS unsigned char* wl, const bf16_t* qb, const bf16_t* kb, const bf16_t* vb, int tq0, int dil, float sl, bf16x8 (&qr)[8], const bf16_t* nqb, const bf16_t* nkb, const bf16_t* nvb, int ntq0, int ndil, ...
;     const int r32 = lane & 31, hi = lane >> 5;
;     LAS unsigned char* kbuf = wl; LAS unsigned char* vbuf = wl + 8192;
;     const int jlo = 64 - tq0 / dil, jhi = 64 + (SEQ - 1 - tq0) / dil;
;     const float lo_i = (float)max(-64, jlo - 64 - r32), hi_i = (float)min(64, jhi - 64 - r32);
;     const bool interior = (jlo <= 0) && (jhi >= 159);
;     float m_run = -1e30f, l_run = 0.f;
;     f32x16 oT[4];
; #pragma unroll
;     for (int d0 = 0; d0 < 4; ++d0)
; #pragma unroll
;         for (int r = 0; r < 16; ++r) oT[d0][r] = 0.f;
;     asm volatile("s_waitcnt vmcnt(0)" ::: "memory");
; #pragma unroll
;     for (int s = 0; s < 8; ++s) asm volatile("" : "+v"(qr[s]));
;     long q8[8];
; #pragma unroll
;     for (int s = 0; s < 8; ++s) q8[s] = bf16x8_to_fp8(qr[s]);
;     f32x2 st1 = {0.f, 0.f}, st2 = {0.f, 0.f};
;     if (FINAL) { const size_t tqs = (size_t)(tq0 + dil * r32) * 2; st1 = *(const GAS f32x2*)(ml0 + tqs); st2 = *(const GAS f32x2*)(ml1 + tqs); }
;     const int rr0 = lane >> 4, cs = lane & 15;
;     const LAS unsigned char* krd = kbuf + r32 * 128 + hi * 8;
;     const int kx = (r32 & 7) << 4;
; #pragma unroll 1
	v_xor_b32_e32 v0, v203, v198
	v_lshlrev_b32_e32 v0, 3, v0
	v_add_u32_e32 v37, 20, v201
	v_and_b32_e32 v170, 0x78, v0
	v_xor_b32_e32 v0, v37, v198
	v_lshlrev_b32_e32 v0, 3, v0
	v_add_u32_e32 v208, 24, v201
	v_and_b32_e32 v172, 0x78, v0
	v_xor_b32_e32 v0, v208, v198
	v_lshlrev_b32_e32 v0, 3, v0
	v_add_u32_e32 v209, 28, v201
	v_and_b32_e32 v174, 0x78, v0
	v_xor_b32_e32 v0, v209, v198
	v_lshlrev_b32_e32 v0, 3, v0
	v_and_b32_e32 v176, 0x78, v0
	v_lshlrev_b32_e32 v0, 8, v200
	v_lshlrev_b32_e32 v4, 4, v198
	s_movk_i32 s8, 0x70
	v_add3_u32 v210, s83, v0, v3
	v_mov_b32_e32 v0, 0xf0
	v_bitop3_b32 v12, v4, s8, v4 bitop3:0xc
	v_bitop3_b32 v18, v4, s8, v0 bitop3:0x6c
	s_movk_i32 s8, 0x80
	v_bitop3_b32 v19, v4, s8, v0 bitop3:0x6c
	s_movk_i32 s8, 0x90
	v_bitop3_b32 v20, v4, s8, v0 bitop3:0x6c
	s_movk_i32 s8, 0xa0
	v_bitop3_b32 v21, v4, s8, v0 bitop3:0x6c
	s_movk_i32 s8, 0xb0
	v_bitop3_b32 v22, v4, s8, v0 bitop3:0x6c
	s_movk_i32 s8, 0xc0
	v_bitop3_b32 v23, v4, s8, v0 bitop3:0x6c
	s_movk_i32 s8, 0xd0
	v_lshlrev_b32_e32 v2, 7, v200
	s_movk_i32 s9, 0x50
	s_movk_i32 s12, 0x60
	v_bitop3_b32 v24, v4, s8, v0 bitop3:0x6c
	s_movk_i32 s8, 0xe0
	v_add3_u32 v2, s83, v2, v3
	v_bitop3_b32 v3, v4, 16, v0 bitop3:0x6c
	v_bitop3_b32 v13, v4, 32, v0 bitop3:0x6c
	v_bitop3_b32 v14, v4, 48, v0 bitop3:0x6c
	v_bitop3_b32 v15, v4, 64, v0 bitop3:0x6c
	v_bitop3_b32 v16, v4, s9, v0 bitop3:0x6c
	v_bitop3_b32 v17, v4, s12, v0 bitop3:0x6c
	v_bitop3_b32 v0, v4, s8, v0 bitop3:0x6c
	v_mov_b32_e32 v6, 0x70
	v_add_u32_e32 v234, v210, v0
	v_mbcnt_hi_u32_b32 v0, -1, v253
	v_and_b32_e32 v5, 0x70, v4
	v_bitop3_b32 v7, v4, 16, v6 bitop3:0x6c
	v_bitop3_b32 v8, v4, 32, v6 bitop3:0x6c
	v_bitop3_b32 v9, v4, 48, v6 bitop3:0x6c
	v_bitop3_b32 v10, v4, 64, v6 bitop3:0x6c
	v_bitop3_b32 v11, v4, s9, v6 bitop3:0x6c
	v_bitop3_b32 v6, v4, s12, v6 bitop3:0x6c
	v_and_b32_e32 v26, 63, v201
	v_and_b32_e32 v0, 64, v0
	v_and_b32_e32 v28, 63, v29
	v_add_u32_e32 v212, v2, v5
	v_add_u32_e32 v213, v2, v7
	v_add_u32_e32 v215, v2, v8
	v_add_u32_e32 v216, v2, v9
	v_add_u32_e32 v217, v2, v10
	v_add_u32_e32 v218, v2, v11
	v_add_u32_e32 v219, v2, v6
	v_add_u32_e32 v220, v2, v12
	v_or_b32_e32 v2, v0, v26
	v_and_b32_e32 v30, 63, v199
	v_lshlrev_b32_e32 v246, 2, v2
	v_or_b32_e32 v2, v0, v28
	v_add_u32_e32 v35, 16, v201
	v_and_b32_e32 v32, 63, v203
	v_lshlrev_b32_e32 v247, 2, v2
	v_or_b32_e32 v2, v0, v30
	v_and_b32_e32 v34, 63, v35
	v_lshlrev_b32_e32 v248, 2, v2
	v_or_b32_e32 v2, v0, v32
	v_and_b32_e32 v36, 63, v37
	v_lshlrev_b32_e32 v249, 2, v2
	v_or_b32_e32 v2, v0, v34
	v_readlane_b32 s17, v254, 3
	s_movk_i32 s13, 0xf0
	v_and_b32_e32 v211, 0xf0, v4
	v_and_b32_e32 v38, 63, v208
	v_and_b32_e32 v40, 63, v209
	v_lshlrev_b32_e32 v250, 2, v2
	v_or_b32_e32 v2, v0, v36
	v_writelane_b32 v254, s16, 32
	v_bitop3_b32 v4, v4, s13, v4 bitop3:0xc
	v_add_u32_e32 v25, s83, v211
	v_lshlrev_b32_e32 v27, 8, v201
	v_lshlrev_b32_e32 v29, 8, v29
	v_lshlrev_b32_e32 v31, 8, v199
	v_lshlrev_b32_e32 v33, 8, v203
	v_lshlrev_b32_e32 v35, 8, v35
	v_lshlrev_b32_e32 v37, 8, v37
	v_lshlrev_b32_e32 v39, 8, v208
	v_lshlrev_b32_e32 v41, 8, v209
	s_mov_b32 s12, 0x41200000
	s_mov_b32 s16, 0x41800000
	s_mov_b32 s18, 0x41900000
	s_mov_b32 s20, 0x41c00000
	s_mov_b32 s22, 0x41d00000
	s_mov_b32 s24, 0x42000000
	s_mov_b32 s26, 0x42080000
	v_lshlrev_b32_e32 v251, 2, v2
	v_or_b32_e32 v2, v0, v38
	v_or_b32_e32 v0, v0, v40
	s_mov_b32 s93, 0x42800000
	s_mov_b32 s14, 0
	s_movk_i32 s97, 0xc00
	v_mov_b32_e32 v165, v1
	v_mov_b32_e32 v167, v1
	v_mov_b32_e32 v169, v1
	v_mov_b32_e32 v171, v1
	v_mov_b32_e32 v173, v1
	v_mov_b32_e32 v175, v1
	v_mov_b32_e32 v177, v1
	s_mov_b32 s92, 0xf149f2ca
	s_mov_b32 s13, 0x41300000
	s_mov_b32 s17, 0x41880000
	s_mov_b32 s19, 0x41980000
	s_mov_b32 s21, 0x41c80000
	s_mov_b32 s23, 0x41d80000
	s_mov_b32 s25, 0x42040000
	s_mov_b32 s27, 0x420c0000
	s_mov_b32 s49, 0xc2800000
	v_add_u32_e32 v221, v210, v3
	v_add_u32_e32 v222, v210, v13
	v_add_u32_e32 v223, v210, v14
	v_add_u32_e32 v224, v210, v15
	v_add_u32_e32 v225, v210, v16
	v_add_u32_e32 v226, v210, v17
	v_add_u32_e32 v227, v210, v18
	v_add_u32_e32 v228, v210, v19
	v_add_u32_e32 v229, v210, v20
	v_add_u32_e32 v230, v210, v21
	v_add_u32_e32 v231, v210, v22
	v_add_u32_e32 v232, v210, v23
	v_add_u32_e32 v233, v210, v24
	v_add_u32_e32 v235, v210, v4
	v_add_u32_e32 v236, v25, v27
	v_add_u32_e32 v237, v25, v29
	v_add_u32_e32 v238, v25, v31
	v_add_u32_e32 v239, v25, v33
	v_add_u32_e32 v240, v25, v35
	v_add_u32_e32 v241, v25, v37
	v_add_u32_e32 v242, v25, v39
	v_add_u32_e32 v243, v25, v41
	v_mov_b32_e32 v244, 0xfff
	v_mov_b32_e32 v245, 0xf149f2ca
	v_lshlrev_b32_e32 v252, 2, v2
	v_lshlrev_b32_e32 v253, 2, v0
	v_mov_b32_e32 v214, 0
	s_mov_b64 s[44:45], s[54:55]
	s_mov_b64 s[42:43], s[6:7]
	s_mov_b64 s[40:41], s[4:5]
	s_mov_b64 s[36:37], s[56:57]
	s_mov_b64 s[34:35], s[58:59]
	s_mov_b64 s[30:31], s[70:71]
	s_mov_b64 s[28:29], s[60:61]
	s_waitcnt vmcnt(0)
	s_branch .LBB0_474

; #define GAS __attribute__((address_space(1)))
; #define LAS __attribute__((address_space(3)))
; __device__ __forceinline__ void attn_unit(const bool FINAL, const bool HN, LAS unsigned char* wl, const bf16_t* qb, const bf16_t* kb, const bf16_t* vb, int tq0, int dil, float sl, bf16x8 (&qr)[8], const bf16_t* nqb, const bf16_t* nkb, const bf16_t* nvb, int ntq0, int ndil, ...
;     const int r32 = lane & 31, hi = lane >> 5;
;     LAS unsigned char* kbuf = wl; LAS unsigned char* vbuf = wl + 8192;
;     const int jlo = 64 - tq0 / dil, jhi = 64 + (SEQ - 1 - tq0) / dil;
;     const float lo_i = (float)max(-64, jlo - 64 - r32), hi_i = (float)min(64, jhi - 64 - r32);
;     const bool interior = (jlo <= 0) && (jhi >= 159);
;     float m_run = -1e30f, l_run = 0.f;
;     f32x16 oT[4];
; #pragma unroll
;     for (int d0 = 0; d0 < 4; ++d0)
; #pragma unroll
;         for (int r = 0; r < 16; ++r) oT[d0][r] = 0.f;
;     asm volatile("s_waitcnt vmcnt(0)" ::: "memory");
; #pragma unroll
;     for (int s = 0; s < 8; ++s) asm volatile("" : "+v"(qr[s]));
;     long q8[8];
; #pragma unroll
;     for (int s = 0; s < 8; ++s) q8[s] = bf16x8_to_fp8(qr[s]);
;     f32x2 st1 = {0.f, 0.f}, st2 = {0.f, 0.f};
;     if (FINAL) { const size_t tqs = (size_t)(tq0 + dil * r32) * 2; st1 = *(const GAS f32x2*)(ml0 + tqs); st2 = *(const GAS f32x2*)(ml1 + tqs); }
;     const int rr0 = lane >> 4, cs = lane & 15;
;     const LAS unsigned char* krd = kbuf + r32 * 128 + hi * 8;
.LBB0_476:
	s_xor_b32 s8, s94, 0xfff
	s_and_b32 s8, s8, 0xffff
	v_add_u32_e32 v0, s94, v200
	v_sub_u32_e32 v2, 0, v0
	v_sub_u32_e32 v3, s8, v200
	v_max_i32_e32 v2, 0xffffffc0, v2
	v_min_u32_e32 v3, 64, v3
	v_cvt_f32_ubyte0_e32 v116, v3
	s_waitcnt vmcnt(12)
	s_waitcnt vmcnt(12)
	v_cvt_f32_i32_e32 v118, v2
	v_lshlrev_b32_e32 v2, 16, v82
	v_and_b32_e32 v3, 0xffff0000, v82
	v_mov_b32_e32 v120, 0
	v_cvt_pk_fp8_f32 v120, v2, v3
	v_lshlrev_b32_e32 v4, 16, v84
	v_and_b32_e32 v5, 0xffff0000, v84
	v_mov_b32_e32 v121, 0
	v_cvt_pk_fp8_f32 v121, v4, v5
	v_lshlrev_b32_e32 v2, 16, v83
	v_and_b32_e32 v3, 0xffff0000, v83
	v_cvt_pk_fp8_f32 v120, v2, v3 op_sel:[0,0,1]
	v_lshlrev_b32_e32 v2, 16, v85
	v_and_b32_e32 v3, 0xffff0000, v85
	v_cvt_pk_fp8_f32 v121, v2, v3 op_sel:[0,0,1]
	v_lshlrev_b32_e32 v2, 16, v86
	v_and_b32_e32 v3, 0xffff0000, v86
	v_mov_b32_e32 v122, 0
	v_cvt_pk_fp8_f32 v122, v2, v3
	v_lshlrev_b32_e32 v4, 16, v88
	v_and_b32_e32 v5, 0xffff0000, v88
	v_mov_b32_e32 v123, 0
	v_cvt_pk_fp8_f32 v123, v4, v5
	v_lshlrev_b32_e32 v2, 16, v87
	v_and_b32_e32 v3, 0xffff0000, v87
	v_cvt_pk_fp8_f32 v122, v2, v3 op_sel:[0,0,1]
	v_lshlrev_b32_e32 v2, 16, v89
	v_and_b32_e32 v3, 0xffff0000, v89
	v_cvt_pk_fp8_f32 v123, v2, v3 op_sel:[0,0,1]
	v_lshlrev_b32_e32 v2, 16, v90
	v_and_b32_e32 v3, 0xffff0000, v90
	v_mov_b32_e32 v124, 0
	v_cvt_pk_fp8_f32 v124, v2, v3
	v_lshlrev_b32_e32 v4, 16, v92
	v_and_b32_e32 v5, 0xffff0000, v92
	v_mov_b32_e32 v125, 0
	v_cvt_pk_fp8_f32 v125, v4, v5
	v_lshlrev_b32_e32 v2, 16, v91
	v_and_b32_e32 v3, 0xffff0000, v91
	v_cvt_pk_fp8_f32 v124, v2, v3 op_sel:[0,0,1]
	v_lshlrev_b32_e32 v2, 16, v93
	v_and_b32_e32 v3, 0xffff0000, v93
	v_cvt_pk_fp8_f32 v125, v2, v3 op_sel:[0,0,1]
	v_lshlrev_b32_e32 v2, 16, v94
	v_and_b32_e32 v3, 0xffff0000, v94
	v_mov_b32_e32 v126, 0
	v_cvt_pk_fp8_f32 v126, v2, v3
	v_lshlrev_b32_e32 v4, 16, v96
	v_and_b32_e32 v5, 0xffff0000, v96
	v_mov_b32_e32 v127, 0
	v_cvt_pk_fp8_f32 v127, v4, v5
	v_lshlrev_b32_e32 v2, 16, v95
	v_and_b32_e32 v3, 0xffff0000, v95
	v_cvt_pk_fp8_f32 v126, v2, v3 op_sel:[0,0,1]
	v_lshlrev_b32_e32 v2, 16, v97
	v_and_b32_e32 v3, 0xffff0000, v97
	v_cvt_pk_fp8_f32 v127, v2, v3 op_sel:[0,0,1]
	v_lshlrev_b32_e32 v2, 16, v98
	v_and_b32_e32 v3, 0xffff0000, v98
	v_mov_b32_e32 v128, 0
	v_lshlrev_b32_e32 v0, 1, v0
	v_cvt_pk_fp8_f32 v128, v2, v3
	v_lshlrev_b64 v[2:3], 2, v[0:1]
	v_lshl_add_u64 v[4:5], s[4:5], 0, v[2:3]
	v_lshl_add_u64 v[2:3], s[6:7], 0, v[2:3]
	global_load_dwordx2 v[180:181], v[4:5], off
	global_load_dwordx2 v[178:179], v[2:3], off
	v_lshlrev_b32_e32 v8, 16, v100
	v_and_b32_e32 v0, 0xffff0000, v100
	v_mov_b32_e32 v129, 0
	v_cvt_pk_fp8_f32 v129, v8, v0
	v_lshlrev_b32_e32 v0, 16, v101
	v_and_b32_e32 v2, 0xffff0000, v101
	v_mov_b32_e32 v130, 0
	v_cvt_pk_fp8_f32 v129, v0, v2 op_sel:[0,0,1]
	v_lshlrev_b32_e32 v0, 16, v102
	v_and_b32_e32 v2, 0xffff0000, v102
	v_cvt_pk_fp8_f32 v130, v0, v2
	v_lshlrev_b32_e32 v3, 16, v104
	v_and_b32_e32 v4, 0xffff0000, v104
	v_mov_b32_e32 v131, 0
	v_cvt_pk_fp8_f32 v131, v3, v4
	v_lshlrev_b32_e32 v0, 16, v103
	v_and_b32_e32 v2, 0xffff0000, v103
	v_cvt_pk_fp8_f32 v130, v0, v2 op_sel:[0,0,1]
	v_lshlrev_b32_e32 v0, 16, v105
	v_and_b32_e32 v2, 0xffff0000, v105
	v_cvt_pk_fp8_f32 v131, v0, v2 op_sel:[0,0,1]
	v_lshlrev_b32_e32 v0, 16, v106
	v_and_b32_e32 v2, 0xffff0000, v106
	v_mov_b32_e32 v132, 0
	v_cvt_pk_fp8_f32 v132, v0, v2
	v_lshlrev_b32_e32 v3, 16, v108
	v_and_b32_e32 v4, 0xffff0000, v108
	v_mov_b32_e32 v133, 0
	v_cvt_pk_fp8_f32 v133, v3, v4
	v_lshlrev_b32_e32 v0, 16, v107
	v_and_b32_e32 v2, 0xffff0000, v107
	v_cvt_pk_fp8_f32 v132, v0, v2 op_sel:[0,0,1]
	v_lshlrev_b32_e32 v0, 16, v109
	v_and_b32_e32 v2, 0xffff0000, v109
	v_cvt_pk_fp8_f32 v133, v0, v2 op_sel:[0,0,1]
	v_lshlrev_b32_e32 v0, 16, v110
	v_and_b32_e32 v2, 0xffff0000, v110
	v_mov_b32_e32 v134, 0
	v_cvt_pk_fp8_f32 v134, v0, v2
	v_lshlrev_b32_e32 v3, 16, v112
	v_and_b32_e32 v4, 0xffff0000, v112
	v_mov_b32_e32 v135, 0
	v_cvt_pk_fp8_f32 v135, v3, v4
	v_lshlrev_b32_e32 v0, 16, v111
	v_and_b32_e32 v2, 0xffff0000, v111
	s_cmpk_gt_u32 s8, 0x5e
	v_lshlrev_b32_e32 v6, 16, v99
	v_and_b32_e32 v7, 0xffff0000, v99
	v_cvt_pk_fp8_f32 v134, v0, v2 op_sel:[0,0,1]
	v_lshlrev_b32_e32 v0, 16, v113
	v_and_b32_e32 v2, 0xffff0000, v113
	s_cselect_b64 s[8:9], -1, 0
	s_cmp_gt_u32 s94, 63
	v_cvt_pk_fp8_f32 v128, v6, v7 op_sel:[0,0,1]
	v_cvt_pk_fp8_f32 v135, v0, v2 op_sel:[0,0,1]
	v_mov_b32_e32 v14, v1
	v_mov_b32_e32 v15, v1
	s_cselect_b64 s[72:73], -1, 0
	v_mov_b32_e32 v0, v1
	v_mov_b32_e32 v2, v1
	v_mov_b32_e32 v3, v1
	v_mov_b32_e32 v4, v1
	v_mov_b32_e32 v5, v1
	v_mov_b32_e32 v6, v1
	v_mov_b32_e32 v7, v1
	v_mov_b32_e32 v8, v1
	v_mov_b32_e32 v9, v1
	v_mov_b32_e32 v10, v1
	v_mov_b32_e32 v11, v1
	v_mov_b32_e32 v12, v1
	v_mov_b32_e32 v13, v1
	v_mov_b64_e32 v[64:65], v[14:15]
	v_mov_b64_e32 v[48:49], v[14:15]
	v_mov_b64_e32 v[32:33], v[14:15]
	s_and_b64 s[72:73], s[72:73], s[8:9]
	v_xor_b32_e32 v136, 0x80000000, v114
	v_mov_b64_e32 v[62:63], v[12:13]
	v_mov_b64_e32 v[60:61], v[10:11]
	v_mov_b64_e32 v[58:59], v[8:9]
	v_mov_b64_e32 v[56:57], v[6:7]
	v_mov_b64_e32 v[54:55], v[4:5]
	v_mov_b64_e32 v[52:53], v[2:3]
	v_mov_b64_e32 v[50:51], v[0:1]
	v_mov_b64_e32 v[46:47], v[12:13]
	v_mov_b64_e32 v[44:45], v[10:11]
	v_mov_b64_e32 v[42:43], v[8:9]
	v_mov_b64_e32 v[40:41], v[6:7]
	v_mov_b64_e32 v[38:39], v[4:5]
	v_mov_b64_e32 v[36:37], v[2:3]
	v_mov_b64_e32 v[34:35], v[0:1]
	v_mov_b64_e32 v[30:31], v[12:13]
	v_mov_b64_e32 v[28:29], v[10:11]
	v_mov_b64_e32 v[26:27], v[8:9]
	v_mov_b64_e32 v[24:25], v[6:7]
	v_mov_b64_e32 v[22:23], v[4:5]
	v_mov_b64_e32 v[20:21], v[2:3]
	v_mov_b64_e32 v[18:19], v[0:1]
	v_mov_b64_e32 v[16:17], v[14:15]
	s_xor_b64 s[74:75], s[72:73], -1
	v_mov_b32_e32 v115, v114
	v_mov_b32_e32 v137, v136
	v_mov_b32_e32 v117, v118
	v_mov_b32_e32 v119, v116
	s_mov_b32 s15, 0
	v_mov_b32_e32 v182, 0xf149f2ca
	v_mov_b32_e32 v156, 0
	v_mov_b64_e32 v[14:15], v[12:13]
	v_mov_b64_e32 v[12:13], v[10:11]
	v_mov_b64_e32 v[10:11], v[8:9]
	v_mov_b64_e32 v[8:9], v[6:7]
	v_mov_b64_e32 v[6:7], v[4:5]
	v_mov_b64_e32 v[4:5], v[2:3]
	v_mov_b64_e32 v[2:3], v[0:1]
	s_mov_b32 s51, 0
	s_cmp_lg_u32 s15, 0
	s_cselect_b64 s[80:81], -1, 0
	s_cmp_eq_u32 s15, 0
	s_cbranch_scc1 .LBB0_478
